# P4 y_off section: coalesced state-row loads + per-wave swizzled LDS transpose, all loads in flight (was 16 dependent load-wait-MFMA steps on 16-byte row pieces)
# speedup vs baseline: 1.0457x; 1.0168x over previous
.LBB0_2121:
	s_or_b64 exec, exec, s[10:11]
	v_mov_b32_e32 v53, 0
	v_mov_b32_e32 v52, 0
	v_mov_b32_e32 v51, 0
	v_mov_b32_e32 v50, 0
	v_mov_b32_e32 v49, 0
	v_mov_b32_e32 v48, 0
	v_mov_b32_e32 v47, 0
	v_mov_b32_e32 v46, 0
	v_mov_b32_e32 v45, 0
	v_mov_b32_e32 v44, 0
	v_mov_b32_e32 v43, 0
	v_mov_b32_e32 v42, 0
	v_mov_b32_e32 v41, 0
	v_mov_b32_e32 v40, 0
	v_mov_b32_e32 v39, 0
	v_mov_b32_e32 v38, 0
	v_mov_b32_e32 v25, 0
	v_mov_b32_e32 v24, 0
	v_mov_b32_e32 v23, 0
	v_mov_b32_e32 v22, 0
	v_mov_b32_e32 v29, 0
	v_mov_b32_e32 v28, 0
	v_mov_b32_e32 v27, 0
	v_mov_b32_e32 v26, 0
	v_mov_b32_e32 v33, 0
	v_mov_b32_e32 v32, 0
	v_mov_b32_e32 v31, 0
	v_mov_b32_e32 v30, 0
	v_mov_b32_e32 v37, 0
	v_mov_b32_e32 v36, 0
	v_mov_b32_e32 v35, 0
	v_mov_b32_e32 v34, 0
	s_and_saveexec_b64 s[22:23], s[20:21]
	v_readlane_b32 s64, v254, 29
	v_readlane_b32 s66, v254, 31
	v_readlane_b32 s67, v254, 32
	v_readlane_b32 s74, v254, 39
	v_readlane_b32 s75, v254, 40
	v_readlane_b32 s65, v254, 30
	v_readlane_b32 s68, v254, 33
	v_readlane_b32 s69, v254, 34
	v_readlane_b32 s70, v254, 35
	v_readlane_b32 s71, v254, 36
	v_readlane_b32 s72, v254, 37
	v_readlane_b32 s73, v254, 38
	v_readlane_b32 s76, v254, 41
	v_readlane_b32 s77, v254, 42
	v_readlane_b32 s78, v254, 43
	v_readlane_b32 s79, v254, 44
	s_cbranch_execz .LBB0_2168
	s_lshl_b32 s78, s29, 8
	s_add_u32 s78, s24, s78
	s_addc_u32 s79, s25, 0
	s_lshl_b32 s10, s9, 7
	s_or_b32 s28, s10, s28
	s_and_b64 s[10:11], exec, s[0:1]
	s_cselect_b32 s10, s28, s9
	s_ashr_i32 s11, s10, 31
	s_lshl_b64 s[10:11], s[10:11], 18
	s_add_u32 s76, s6, s10
	s_addc_u32 s77, s7, s11
	v_lshrrev_b32_e32 v148, 6, v0
	v_lshlrev_b32_e32 v149, 4, v137
	v_or_b32_e32 v149, v149, v134
	v_readfirstlane_b32 s10, v4
	v_readfirstlane_b32 s73, v148
	s_lshl_b32 s10, s10, 15
	s_add_u32 s76, s76, s10
	s_addc_u32 s77, s77, 0
	s_lshl_b32 s73, s73, 13
	s_add_i32 s73, s73, 0x800
	v_lshrrev_b32_e32 v150, 3, v149
	v_and_b32_e32 v151, 7, v149
	v_lshlrev_b32_e32 v152, 9, v150
	v_lshl_add_u32 v152, v151, 4, v152
	v_add_u32_e32 v153, 0x1000, v152
	v_add_u32_e32 v154, 0x2000, v152
	v_add_u32_e32 v155, 0x3000, v152
	v_add_u32_e32 v156, 0x4000, v152
	v_add_u32_e32 v157, 0x5000, v152
	v_add_u32_e32 v158, 0x6000, v152
	v_add_u32_e32 v159, 0x7000, v152
	v_lshlrev_b32_e32 v164, 4, v137
	v_mov_b32_e32 v165, 0
	v_lshl_add_u64 v[166:167], s[78:79], 0, v[164:165]
	v_lshlrev_b64 v[148:149], 9, v[70:71]
	v_lshl_add_u64 v[148:149], v[166:167], 0, v[148:149]
	global_load_dwordx4 v[200:203], v[148:149], off
	global_load_dwordx4 v[204:207], v[148:149], off offset:64
	global_load_dwordx4 v[208:211], v[148:149], off offset:128
	global_load_dwordx4 v[212:215], v[148:149], off offset:192
	s_and_b64 vcc, exec, s[0:1]
	s_cbranch_vccz .Lp4_nocb0
	v_lshlrev_b64 v[148:149], 9, v[68:69]
	v_lshl_add_u64 v[148:149], v[166:167], 0, v[148:149]
	global_load_dwordx4 v[168:171], v[148:149], off
	global_load_dwordx4 v[172:175], v[148:149], off offset:64
	global_load_dwordx4 v[176:179], v[148:149], off offset:128
	global_load_dwordx4 v[180:183], v[148:149], off offset:192
	s_branch .Lp4_cbdone
.Lp4_nocb0:
	v_mov_b32_e32 v168, 0
	v_mov_b32_e32 v169, 0
	v_mov_b32_e32 v170, 0
	v_mov_b32_e32 v171, 0
	v_mov_b32_e32 v172, 0
	v_mov_b32_e32 v173, 0
	v_mov_b32_e32 v174, 0
	v_mov_b32_e32 v175, 0
	v_mov_b32_e32 v176, 0
	v_mov_b32_e32 v177, 0
	v_mov_b32_e32 v178, 0
	v_mov_b32_e32 v179, 0
	v_mov_b32_e32 v180, 0
	v_mov_b32_e32 v181, 0
	v_mov_b32_e32 v182, 0
	v_mov_b32_e32 v183, 0
.Lp4_cbdone:
	global_load_dwordx4 v[216:219], v152, s[76:77]
	global_load_dwordx4 v[220:223], v153, s[76:77]
	global_load_dwordx4 v[224:227], v154, s[76:77]
	global_load_dwordx4 v[228:231], v155, s[76:77]
	global_load_dwordx4 v[232:235], v156, s[76:77]
	global_load_dwordx4 v[236:239], v157, s[76:77]
	global_load_dwordx4 v[240:243], v158, s[76:77]
	global_load_dwordx4 v[244:247], v159, s[76:77]
	global_load_dwordx4 v[54:57], v152, s[76:77] offset:128
	global_load_dwordx4 v[58:61], v153, s[76:77] offset:128
	global_load_dwordx4 v[62:65], v154, s[76:77] offset:128
	global_load_dwordx4 v[120:123], v155, s[76:77] offset:128
	global_load_dwordx4 v[124:127], v156, s[76:77] offset:128
	global_load_dwordx4 v[128:131], v157, s[76:77] offset:128
	global_load_dwordx4 v[140:143], v158, s[76:77] offset:128
	global_load_dwordx4 v[144:147], v159, s[76:77] offset:128
	v_bfe_u32 v160, v150, 1, 1
	v_bfe_u32 v163, v150, 2, 1
	v_lshl_or_b32 v160, v163, 2, v160
	v_xor_b32_e32 v160, v160, v151
	v_lshlrev_b32_e32 v160, 4, v160
	v_lshl_add_u32 v160, v150, 7, v160
	v_add_u32_e32 v160, s73, v160
	v_bfe_u32 v161, v134, 1, 1
	v_bfe_u32 v163, v134, 2, 1
	v_lshl_or_b32 v161, v163, 2, v161
	v_lshlrev_b32_e32 v163, 1, v137
	v_xor_b32_e32 v161, v161, v163
	v_lshlrev_b32_e32 v161, 4, v161
	v_lshl_add_u32 v161, v134, 7, v161
	v_add_u32_e32 v161, s73, v161
	v_xor_b32_e32 v162, 16, v161
	s_waitcnt vmcnt(8)
	ds_write_b128 v160, v[216:219]
	ds_write_b128 v160, v[220:223] offset:1024
	ds_write_b128 v160, v[224:227] offset:2048
	ds_write_b128 v160, v[228:231] offset:3072
	ds_write_b128 v160, v[232:235] offset:4096
	ds_write_b128 v160, v[236:239] offset:5120
	ds_write_b128 v160, v[240:243] offset:6144
	ds_write_b128 v160, v[244:247] offset:7168
	global_load_dwordx4 v[216:219], v152, s[76:77] offset:256
	global_load_dwordx4 v[220:223], v153, s[76:77] offset:256
	global_load_dwordx4 v[224:227], v154, s[76:77] offset:256
	global_load_dwordx4 v[228:231], v155, s[76:77] offset:256
	global_load_dwordx4 v[232:235], v156, s[76:77] offset:256
	global_load_dwordx4 v[236:239], v157, s[76:77] offset:256
	global_load_dwordx4 v[240:243], v158, s[76:77] offset:256
	global_load_dwordx4 v[244:247], v159, s[76:77] offset:256
	ds_read_b128 v[184:187], v161
	ds_read_b128 v[188:191], v162
	s_waitcnt lgkmcnt(0)
	v_cvt_pk_bf16_f32 v192, v184, v185
	v_cvt_pk_bf16_f32 v193, v186, v187
	v_cvt_pk_bf16_f32 v194, v188, v189
	v_cvt_pk_bf16_f32 v195, v190, v191
	s_nop 1
	v_mfma_f32_16x16x32_bf16 v[22:25], v[192:195], v[168:171], v[22:25]
	v_mfma_f32_16x16x32_bf16 v[38:41], v[192:195], v[200:203], v[38:41]
	ds_read_b128 v[184:187], v161 offset:2048
	ds_read_b128 v[188:191], v162 offset:2048
	s_waitcnt lgkmcnt(0)
	v_cvt_pk_bf16_f32 v192, v184, v185
	v_cvt_pk_bf16_f32 v193, v186, v187
	v_cvt_pk_bf16_f32 v194, v188, v189
	v_cvt_pk_bf16_f32 v195, v190, v191
	s_nop 1
	v_mfma_f32_16x16x32_bf16 v[26:29], v[192:195], v[168:171], v[26:29]
	v_mfma_f32_16x16x32_bf16 v[42:45], v[192:195], v[200:203], v[42:45]
	ds_read_b128 v[184:187], v161 offset:4096
	ds_read_b128 v[188:191], v162 offset:4096
	s_waitcnt lgkmcnt(0)
	v_cvt_pk_bf16_f32 v192, v184, v185
	v_cvt_pk_bf16_f32 v193, v186, v187
	v_cvt_pk_bf16_f32 v194, v188, v189
	v_cvt_pk_bf16_f32 v195, v190, v191
	s_nop 1
	v_mfma_f32_16x16x32_bf16 v[30:33], v[192:195], v[168:171], v[30:33]
	v_mfma_f32_16x16x32_bf16 v[46:49], v[192:195], v[200:203], v[46:49]
	ds_read_b128 v[184:187], v161 offset:6144
	ds_read_b128 v[188:191], v162 offset:6144
	s_waitcnt lgkmcnt(0)
	v_cvt_pk_bf16_f32 v192, v184, v185
	v_cvt_pk_bf16_f32 v193, v186, v187
	v_cvt_pk_bf16_f32 v194, v188, v189
	v_cvt_pk_bf16_f32 v195, v190, v191
	s_nop 1
	v_mfma_f32_16x16x32_bf16 v[34:37], v[192:195], v[168:171], v[34:37]
	v_mfma_f32_16x16x32_bf16 v[50:53], v[192:195], v[200:203], v[50:53]
	s_waitcnt vmcnt(8)
	ds_write_b128 v160, v[54:57]
	ds_write_b128 v160, v[58:61] offset:1024
	ds_write_b128 v160, v[62:65] offset:2048
	ds_write_b128 v160, v[120:123] offset:3072
	ds_write_b128 v160, v[124:127] offset:4096
	ds_write_b128 v160, v[128:131] offset:5120
	ds_write_b128 v160, v[140:143] offset:6144
	ds_write_b128 v160, v[144:147] offset:7168
	global_load_dwordx4 v[54:57], v152, s[76:77] offset:384
	global_load_dwordx4 v[58:61], v153, s[76:77] offset:384
	global_load_dwordx4 v[62:65], v154, s[76:77] offset:384
	global_load_dwordx4 v[120:123], v155, s[76:77] offset:384
	global_load_dwordx4 v[124:127], v156, s[76:77] offset:384
	global_load_dwordx4 v[128:131], v157, s[76:77] offset:384
	global_load_dwordx4 v[140:143], v158, s[76:77] offset:384
	global_load_dwordx4 v[144:147], v159, s[76:77] offset:384
	ds_read_b128 v[184:187], v161
	ds_read_b128 v[188:191], v162
	s_waitcnt lgkmcnt(0)
	v_cvt_pk_bf16_f32 v192, v184, v185
	v_cvt_pk_bf16_f32 v193, v186, v187
	v_cvt_pk_bf16_f32 v194, v188, v189
	v_cvt_pk_bf16_f32 v195, v190, v191
	s_nop 1
	v_mfma_f32_16x16x32_bf16 v[22:25], v[192:195], v[172:175], v[22:25]
	v_mfma_f32_16x16x32_bf16 v[38:41], v[192:195], v[204:207], v[38:41]
	ds_read_b128 v[184:187], v161 offset:2048
	ds_read_b128 v[188:191], v162 offset:2048
	s_waitcnt lgkmcnt(0)
	v_cvt_pk_bf16_f32 v192, v184, v185
	v_cvt_pk_bf16_f32 v193, v186, v187
	v_cvt_pk_bf16_f32 v194, v188, v189
	v_cvt_pk_bf16_f32 v195, v190, v191
	s_nop 1
	v_mfma_f32_16x16x32_bf16 v[26:29], v[192:195], v[172:175], v[26:29]
	v_mfma_f32_16x16x32_bf16 v[42:45], v[192:195], v[204:207], v[42:45]
	ds_read_b128 v[184:187], v161 offset:4096
	ds_read_b128 v[188:191], v162 offset:4096
	s_waitcnt lgkmcnt(0)
	v_cvt_pk_bf16_f32 v192, v184, v185
	v_cvt_pk_bf16_f32 v193, v186, v187
	v_cvt_pk_bf16_f32 v194, v188, v189
	v_cvt_pk_bf16_f32 v195, v190, v191
	s_nop 1
	v_mfma_f32_16x16x32_bf16 v[30:33], v[192:195], v[172:175], v[30:33]
	v_mfma_f32_16x16x32_bf16 v[46:49], v[192:195], v[204:207], v[46:49]
	ds_read_b128 v[184:187], v161 offset:6144
	ds_read_b128 v[188:191], v162 offset:6144
	s_waitcnt lgkmcnt(0)
	v_cvt_pk_bf16_f32 v192, v184, v185
	v_cvt_pk_bf16_f32 v193, v186, v187
	v_cvt_pk_bf16_f32 v194, v188, v189
	v_cvt_pk_bf16_f32 v195, v190, v191
	s_nop 1
	v_mfma_f32_16x16x32_bf16 v[34:37], v[192:195], v[172:175], v[34:37]
	v_mfma_f32_16x16x32_bf16 v[50:53], v[192:195], v[204:207], v[50:53]
	s_waitcnt vmcnt(8)
	ds_write_b128 v160, v[216:219]
	ds_write_b128 v160, v[220:223] offset:1024
	ds_write_b128 v160, v[224:227] offset:2048
	ds_write_b128 v160, v[228:231] offset:3072
	ds_write_b128 v160, v[232:235] offset:4096
	ds_write_b128 v160, v[236:239] offset:5120
	ds_write_b128 v160, v[240:243] offset:6144
	ds_write_b128 v160, v[244:247] offset:7168
	ds_read_b128 v[184:187], v161
	ds_read_b128 v[188:191], v162
	s_waitcnt lgkmcnt(0)
	v_cvt_pk_bf16_f32 v192, v184, v185
	v_cvt_pk_bf16_f32 v193, v186, v187
	v_cvt_pk_bf16_f32 v194, v188, v189
	v_cvt_pk_bf16_f32 v195, v190, v191
	s_nop 1
	v_mfma_f32_16x16x32_bf16 v[22:25], v[192:195], v[176:179], v[22:25]
	v_mfma_f32_16x16x32_bf16 v[38:41], v[192:195], v[208:211], v[38:41]
	ds_read_b128 v[184:187], v161 offset:2048
	ds_read_b128 v[188:191], v162 offset:2048
	s_waitcnt lgkmcnt(0)
	v_cvt_pk_bf16_f32 v192, v184, v185
	v_cvt_pk_bf16_f32 v193, v186, v187
	v_cvt_pk_bf16_f32 v194, v188, v189
	v_cvt_pk_bf16_f32 v195, v190, v191
	s_nop 1
	v_mfma_f32_16x16x32_bf16 v[26:29], v[192:195], v[176:179], v[26:29]
	v_mfma_f32_16x16x32_bf16 v[42:45], v[192:195], v[208:211], v[42:45]
	ds_read_b128 v[184:187], v161 offset:4096
	ds_read_b128 v[188:191], v162 offset:4096
	s_waitcnt lgkmcnt(0)
	v_cvt_pk_bf16_f32 v192, v184, v185
	v_cvt_pk_bf16_f32 v193, v186, v187
	v_cvt_pk_bf16_f32 v194, v188, v189
	v_cvt_pk_bf16_f32 v195, v190, v191
	s_nop 1
	v_mfma_f32_16x16x32_bf16 v[30:33], v[192:195], v[176:179], v[30:33]
	v_mfma_f32_16x16x32_bf16 v[46:49], v[192:195], v[208:211], v[46:49]
	ds_read_b128 v[184:187], v161 offset:6144
	ds_read_b128 v[188:191], v162 offset:6144
	s_waitcnt lgkmcnt(0)
	v_cvt_pk_bf16_f32 v192, v184, v185
	v_cvt_pk_bf16_f32 v193, v186, v187
	v_cvt_pk_bf16_f32 v194, v188, v189
	v_cvt_pk_bf16_f32 v195, v190, v191
	s_nop 1
	v_mfma_f32_16x16x32_bf16 v[34:37], v[192:195], v[176:179], v[34:37]
	v_mfma_f32_16x16x32_bf16 v[50:53], v[192:195], v[208:211], v[50:53]
	s_waitcnt vmcnt(0)
	ds_write_b128 v160, v[54:57]
	ds_write_b128 v160, v[58:61] offset:1024
	ds_write_b128 v160, v[62:65] offset:2048
	ds_write_b128 v160, v[120:123] offset:3072
	ds_write_b128 v160, v[124:127] offset:4096
	ds_write_b128 v160, v[128:131] offset:5120
	ds_write_b128 v160, v[140:143] offset:6144
	ds_write_b128 v160, v[144:147] offset:7168
	ds_read_b128 v[184:187], v161
	ds_read_b128 v[188:191], v162
	s_waitcnt lgkmcnt(0)
	v_cvt_pk_bf16_f32 v192, v184, v185
	v_cvt_pk_bf16_f32 v193, v186, v187
	v_cvt_pk_bf16_f32 v194, v188, v189
	v_cvt_pk_bf16_f32 v195, v190, v191
	s_nop 1
	v_mfma_f32_16x16x32_bf16 v[22:25], v[192:195], v[180:183], v[22:25]
	v_mfma_f32_16x16x32_bf16 v[38:41], v[192:195], v[212:215], v[38:41]
	ds_read_b128 v[184:187], v161 offset:2048
	ds_read_b128 v[188:191], v162 offset:2048
	s_waitcnt lgkmcnt(0)
	v_cvt_pk_bf16_f32 v192, v184, v185
	v_cvt_pk_bf16_f32 v193, v186, v187
	v_cvt_pk_bf16_f32 v194, v188, v189
	v_cvt_pk_bf16_f32 v195, v190, v191
	s_nop 1
	v_mfma_f32_16x16x32_bf16 v[26:29], v[192:195], v[180:183], v[26:29]
	v_mfma_f32_16x16x32_bf16 v[42:45], v[192:195], v[212:215], v[42:45]
	ds_read_b128 v[184:187], v161 offset:4096
	ds_read_b128 v[188:191], v162 offset:4096
	s_waitcnt lgkmcnt(0)
	v_cvt_pk_bf16_f32 v192, v184, v185
	v_cvt_pk_bf16_f32 v193, v186, v187
	v_cvt_pk_bf16_f32 v194, v188, v189
	v_cvt_pk_bf16_f32 v195, v190, v191
	s_nop 1
	v_mfma_f32_16x16x32_bf16 v[30:33], v[192:195], v[180:183], v[30:33]
	v_mfma_f32_16x16x32_bf16 v[46:49], v[192:195], v[212:215], v[46:49]
	ds_read_b128 v[184:187], v161 offset:6144
	ds_read_b128 v[188:191], v162 offset:6144
	s_waitcnt lgkmcnt(0)
	v_cvt_pk_bf16_f32 v192, v184, v185
	v_cvt_pk_bf16_f32 v193, v186, v187
	v_cvt_pk_bf16_f32 v194, v188, v189
	v_cvt_pk_bf16_f32 v195, v190, v191
	s_nop 1
	v_mfma_f32_16x16x32_bf16 v[34:37], v[192:195], v[180:183], v[34:37]
	v_mfma_f32_16x16x32_bf16 v[50:53], v[192:195], v[212:215], v[50:53]
	s_nop 7
	s_nop 1
